# attention tail: fast path for the common no-rescale case (wave-uniform test shortened, slow path and rescale block moved out of line)
# speedup vs baseline: 1.0053x; 1.0053x over previous
; __device__ __forceinline__ void finishSM(f32x16& p0, f32x16& p1, float alpha, float& l_reg, bf16x8& pa0, bf16x8& pa1, bf16x8& pa2, bf16x8& pa3) {
; #pragma unroll
;     for (int r = 0; r < 16; ++r) p1[r] = __builtin_amdgcn_exp2f(p1[r]);
;     float ps = 0;
; #pragma unroll
;     for (int r = 0; r < 16; ++r) ps += p0[r];
; #pragma unroll
;     for (int r = 0; r < 16; ++r) ps += p1[r];
;     { auto rr = __builtin_amdgcn_permlane32_swap(__float_as_uint(ps), __float_as_uint(ps), false, false);
;       ps = __uint_as_float(rr[0]) + __uint_as_float(rr[1]); }
;     l_reg = l_reg * alpha + ps;
;     ...
;     PK4(p0, 0, pa0); PK4(p0, 8, pa1); PK4(p1, 0, pa2); PK4(p1, 8, pa3);
;     ...
; }
; __device__ __forceinline__ void qkt(f32x16& p0, f32x16& p1, const char* Kn, const bf16x8* qr, int r32, int hi) {
;     const char* Kr = Kn + KR_OFF;
;     p0 = f32x16{}; p1 = f32x16{};
;     __builtin_amdgcn_s_setprio(1);
; #pragma unroll
;     for (int d0 = 0; d0 < 8; ++d0) { const int cb = (d0 * 16 + hi * 8) * 2;
;         const bf16x8 b0 = *reinterpret_cast<const bf16x8*>(Kn + KNSWZ(r32, cb));
;         const bf16x8 b1 = *reinterpret_cast<const bf16x8*>(Kn + KNSWZ(32 + r32, cb));
;         p0 = __builtin_amdgcn_mfma_f32_32x32x16_bf16(b0, qr[d0], p0, 0, 0, 0);
;         p1 = __builtin_amdgcn_mfma_f32_32x32x16_bf16(b1, qr[d0], p1, 0, 0, 0); }
; #pragma unroll
;     for (int d0 = 0; d0 < 4; ++d0) { const int cb = (d0 * 16 + hi * 8) * 2;
;         const bf16x8 b0 = *reinterpret_cast<const bf16x8*>(Kr + KRSWZ(r32, cb));
;         const bf16x8 b1 = *reinterpret_cast<const bf16x8*>(Kr + KRSWZ(32 + r32, cb));
;         p0 = __builtin_amdgcn_mfma_f32_32x32x16_bf16(b0, qr[8 + d0], p0, 0, 0, 0);
;         p1 = __builtin_amdgcn_mfma_f32_32x32x16_bf16(b1, qr[8 + d0], p1, 0, 0, 0); }
; }
.LBB0_216:
	s_mul_i32 s0, s9, 0x6000
	s_add_i32 s14, s0, 0
	s_lshl_b32 s13, s9, 14
	s_add_i32 s16, s14, s6
	s_add_i32 s17, s7, s13
	s_add_i32 s18, s14, s8
	s_mov_b32 s13, s10
	s_mov_b32 s10, s15
	s_mul_i32 s0, s13, 0x6000
	s_add_i32 s0, s0, 0
	s_setprio 1
	v_add_u32_e32 v84, s0, v207
	ds_read_b128 v[80:83], v84
	ds_read_b128 v[84:87], v84 offset:8192
	v_add_u32_e32 v168, s0, v210
	ds_read_b128 v[196:199], v168
	ds_read_b128 v[168:171], v168 offset:8192
	v_add_u32_e32 v184, s0, v218
	s_waitcnt lgkmcnt(0)
	v_mfma_f32_32x32x16_bf16 v[96:111], v[80:83], v[156:159], 0
	v_mfma_f32_32x32x16_bf16 v[80:95], v[84:87], v[156:159], 0
	v_mfma_f32_32x32x16_bf16 v[96:111], v[196:199], v[152:155], v[96:111]
	v_mfma_f32_32x32x16_bf16 v[80:95], v[168:171], v[152:155], v[80:95]
	ds_read_b128 v[168:171], v184
	ds_read_b128 v[196:199], v184 offset:8192
	v_add_u32_e32 v184, s0, v221
	s_mov_b32 m0, s16
	s_add_u32 s100, s72, 0x26500000
	s_addc_u32 s101, s73, 0
	global_load_lds_dwordx4 v178, s[100:101]
	s_waitcnt lgkmcnt(0)
	v_mfma_f32_32x32x16_bf16 v[96:111], v[168:171], v[148:151], v[96:111]
	v_mfma_f32_32x32x16_bf16 v[80:95], v[196:199], v[148:151], v[80:95]
	ds_read_b128 v[168:171], v184
	ds_read_b128 v[196:199], v184 offset:8192
	v_add_u32_e32 v184, s0, v222
	s_waitcnt lgkmcnt(0)
	v_mfma_f32_32x32x16_bf16 v[96:111], v[168:171], v[144:147], v[96:111]
	v_mfma_f32_32x32x16_bf16 v[80:95], v[196:199], v[144:147], v[80:95]
	ds_read_b128 v[168:171], v184
	ds_read_b128 v[196:199], v184 offset:8192
	v_add_u32_e32 v184, s0, v223
	s_add_i32 m0, s16, 0x400
	s_nop 0
	global_load_lds_dwordx4 v180, s[100:101]
	s_waitcnt lgkmcnt(0)
	v_mfma_f32_32x32x16_bf16 v[96:111], v[168:171], v[140:143], v[96:111]
	v_mfma_f32_32x32x16_bf16 v[80:95], v[196:199], v[140:143], v[80:95]
	ds_read_b128 v[168:171], v184
	ds_read_b128 v[196:199], v184 offset:8192
	v_add_u32_e32 v184, s0, v224
	v_exp_f32_e32 v233, v73
	s_waitcnt lgkmcnt(0)
	v_mfma_f32_32x32x16_bf16 v[96:111], v[168:171], v[136:139], v[96:111]
	v_mfma_f32_32x32x16_bf16 v[80:95], v[196:199], v[136:139], v[80:95]
	ds_read_b128 v[168:171], v184
	ds_read_b128 v[196:199], v184 offset:8192
	v_add_u32_e32 v184, s0, v225
	s_mov_b32 m0, s17
	s_add_u32 s100, s72, 0x26500100
	s_addc_u32 s101, s73, 0
	global_load_lds_dwordx4 v176, s[100:101]
	v_exp_f32_e32 v250, v74
	s_waitcnt lgkmcnt(0)
	v_mfma_f32_32x32x16_bf16 v[96:111], v[168:171], v[132:135], v[96:111]
	v_mfma_f32_32x32x16_bf16 v[80:95], v[196:199], v[132:135], v[80:95]
	ds_read_b128 v[168:171], v184
	ds_read_b128 v[196:199], v184 offset:8192
	v_add_u32_e32 v184, s0, v226
	v_exp_f32_e32 v200, v75
	s_waitcnt lgkmcnt(0)
	v_mfma_f32_32x32x16_bf16 v[96:111], v[168:171], v[128:131], v[96:111]
	v_mfma_f32_32x32x16_bf16 v[80:95], v[196:199], v[128:131], v[80:95]
	ds_read_b128 v[168:171], v184 offset:16384
	ds_read_b128 v[196:199], v184 offset:20480
	v_add_u32_e32 v184, s0, v227
	s_add_i32 m0, s17, 0x400
	s_add_u32 s100, s72, 0x26500180
	s_addc_u32 s101, s73, 0
	global_load_lds_dwordx4 v176, s[100:101]
	v_exp_f32_e32 v195, v76
	s_waitcnt lgkmcnt(0)
	v_mfma_f32_32x32x16_bf16 v[96:111], v[168:171], v[124:127], v[96:111]
	v_mfma_f32_32x32x16_bf16 v[80:95], v[196:199], v[124:127], v[80:95]
	ds_read_b128 v[168:171], v184 offset:16384
	ds_read_b128 v[196:199], v184 offset:20480
	v_add_u32_e32 v184, s0, v228
	v_exp_f32_e32 v172, v77
	s_waitcnt lgkmcnt(0)
	v_mfma_f32_32x32x16_bf16 v[96:111], v[168:171], v[120:123], v[96:111]
	v_mfma_f32_32x32x16_bf16 v[80:95], v[196:199], v[120:123], v[80:95]
	ds_read_b128 v[168:171], v184 offset:16384
	ds_read_b128 v[196:199], v184 offset:20480
	v_add_u32_e32 v184, s0, v229
	s_add_i32 m0, s18, 0x4000
	s_add_u32 s100, s72, 0x21204000
	s_addc_u32 s101, s73, 0
	global_load_lds_dwordx4 v174, s[100:101]
	v_exp_f32_e32 v173, v78
	s_waitcnt lgkmcnt(0)
	v_mfma_f32_32x32x16_bf16 v[96:111], v[168:171], v[116:119], v[96:111]
	v_mfma_f32_32x32x16_bf16 v[80:95], v[196:199], v[116:119], v[80:95]
	ds_read_b128 v[168:171], v184 offset:16384
	ds_read_b128 v[196:199], v184 offset:20480
	v_exp_f32_e32 v184, v68
	v_exp_f32_e32 v79, v79
	s_waitcnt lgkmcnt(0)
	v_mfma_f32_32x32x16_bf16 v[96:111], v[168:171], v[112:115], v[96:111]
	v_exp_f32_e32 v168, v64
	v_add_f32_e32 v64, 0, v247
	v_add_f32_e32 v64, v249, v64
	v_add_f32_e32 v64, v245, v64
	v_add_f32_e32 v64, v248, v64
	v_add_f32_e32 v64, v244, v64
	v_add_f32_e32 v64, v246, v64
	v_add_f32_e32 v64, v242, v64
	v_add_f32_e32 v64, v243, v64
	v_add_f32_e32 v64, v239, v64
	v_add_f32_e32 v64, v241, v64
	v_add_f32_e32 v64, v238, v64
	v_add_f32_e32 v64, v240, v64
	v_add_f32_e32 v64, v235, v64
	v_exp_f32_e32 v169, v65
	v_add_f32_e32 v64, v237, v64
	v_exp_f32_e32 v170, v66
	v_add_f32_e32 v64, v234, v64
	v_exp_f32_e32 v171, v67
	v_add_f32_e32 v64, v236, v64
	v_add_f32_e32 v64, v168, v64
	v_mfma_f32_32x32x16_bf16 v[80:95], v[196:199], v[112:115], v[80:95]
	v_exp_f32_e32 v196, v69
	v_add_f32_e32 v64, v169, v64
	v_exp_f32_e32 v197, v70
	v_add_f32_e32 v64, v170, v64
	v_exp_f32_e32 v198, v71
	v_add_f32_e32 v64, v171, v64
	v_exp_f32_e32 v199, v72
	v_add_f32_e32 v64, v184, v64
	v_add_f32_e32 v64, v196, v64
	v_add_f32_e32 v64, v197, v64
	v_add_f32_e32 v64, v198, v64
	v_add_f32_e32 v64, v199, v64
	v_add_f32_e32 v64, v233, v64
	v_add_f32_e32 v64, v250, v64
	v_add_f32_e32 v64, v200, v64
	v_add_f32_e32 v64, v195, v64
	v_add_f32_e32 v64, v172, v64
	v_add_f32_e32 v64, v173, v64
	v_add_f32_e32 v231, v79, v64
	v_mov_b32_e32 v232, v231
	v_cvt_pk_bf16_f32 v64, v247, v249
	v_cvt_pk_bf16_f32 v65, v245, v248
	v_cvt_pk_bf16_f32 v66, v244, v246
	s_nop 1
	v_permlane32_swap_b32_e32 v231, v232
	v_cvt_pk_bf16_f32 v67, v242, v243
	v_permlane32_swap_b32_e32 v64, v66
	v_cvt_pk_bf16_f32 v68, v239, v241
	v_cvt_pk_bf16_f32 v69, v238, v240
	v_cvt_pk_bf16_f32 v70, v235, v237
	v_cvt_pk_bf16_f32 v71, v234, v236
	v_cvt_pk_bf16_f32 v72, v168, v169
	v_cvt_pk_bf16_f32 v73, v170, v171
	v_cvt_pk_bf16_f32 v74, v184, v196
	v_cvt_pk_bf16_f32 v75, v197, v198
	v_cvt_pk_bf16_f32 v76, v199, v233
	v_cvt_pk_bf16_f32 v77, v250, v200
	v_cvt_pk_bf16_f32 v78, v195, v172
	v_cvt_pk_bf16_f32 v79, v173, v79
	v_permlane32_swap_b32_e32 v65, v67
	v_permlane32_swap_b32_e32 v68, v70
	v_permlane32_swap_b32_e32 v69, v71
	v_permlane32_swap_b32_e32 v72, v74
	v_permlane32_swap_b32_e32 v73, v75
	v_permlane32_swap_b32_e32 v76, v78
	v_permlane32_swap_b32_e32 v77, v79
	s_setprio 0
	s_lshl_b32 s15, s15, 14
	v_add_u32_e32 v172, s15, v205
	ds_read_b64_tr_b16 v[168:169], v172 offset:0
	ds_read_b64_tr_b16 v[170:171], v172 offset:0x800
	ds_read_b64_tr_b16 v[196:197], v172 offset:0x1000
	ds_read_b64_tr_b16 v[198:199], v172 offset:0x1800
	ds_read_b64_tr_b16 v[234:235], v172 offset:0x2000
	ds_read_b64_tr_b16 v[236:237], v172 offset:0x2800
	ds_read_b64_tr_b16 v[238:239], v172 offset:0x3000
	ds_read_b64_tr_b16 v[240:241], v172 offset:0x3800
	s_waitcnt lgkmcnt(0)
; #define SBAR() __builtin_amdgcn_sched_barrier(0)
; template <bool FIRST>
; __device__ __forceinline__ void partialSM(f32x16& p0, f32x16& p1, float& m_reg, float& mn, float& alpha) {
;     float pmax = p0[0];
; #pragma unroll
;     for (int r = 1; r < 16; ++r) pmax = fmaxf(pmax, p0[r]);
; #pragma unroll
;     for (int r = 0; r < 16; ++r) pmax = fmaxf(pmax, p1[r]);
;     { auto rr = __builtin_amdgcn_permlane32_swap(__float_as_uint(pmax), __float_as_uint(pmax), false, false);
;       pmax = fmaxf(__uint_as_float(rr[0]), __uint_as_float(rr[1])); }
;     if (FIRST) { mn = (fabsf(pmax) <= THRL) ? 0.f : pmax; m_reg = mn; alpha = 1.f; }
;     else if (__builtin_expect(__all(pmax - m_reg <= THRL), 1)) { mn = m_reg; alpha = 1.f; }
;     else { mn = fmaxf(m_reg, pmax); alpha = __builtin_amdgcn_exp2f(m_reg - mn); m_reg = mn; }
;     if (!__builtin_expect(__all(mn == 0.f), 1)) {
; #pragma unroll
;         for (int r = 0; r < 16; ++r) p0[r] = p0[r] - mn;
; #pragma unroll
;         for (int r = 0; r < 16; ++r) p1[r] = p1[r] - mn; }
; #pragma unroll
;     for (int r = 0; r < 16; ++r) p0[r] = __builtin_amdgcn_exp2f(p0[r]);
; }
; template <int D0> __device__ __forceinline__ void pv_one(f32x16& od, int vb, bf16x8 pa0, bf16x8 pa1, bf16x8 pa2, bf16x8 pa3) {
;     const s16x4 l0 = tr_read<v_rd_off(D0, 0, 0)>(vb), h0 = tr_read<v_rd_off(D0, 0, 1)>(vb), l1 = tr_read<v_rd_off(D0, 1, 0)>(vb), h1 = tr_read<v_rd_off(D0, 1, 1)>(vb);
;     const s16x4 l2 = tr_read<v_rd_off(D0, 2, 0)>(vb), h2 = tr_read<v_rd_off(D0, 2, 1)>(vb), l3 = tr_read<v_rd_off(D0, 3, 0)>(vb), h3 = tr_read<v_rd_off(D0, 3, 1)>(vb);
;     asm volatile("s_waitcnt lgkmcnt(0)" ::: "memory"); SBAR();
;     ...
;     od = __builtin_amdgcn_mfma_f32_32x32x16_bf16(pa0, PK(l0, h0), od, 0, 0, 0);
;     od = __builtin_amdgcn_mfma_f32_32x32x16_bf16(pa1, PK(l1, h1), od, 0, 0, 0);
;     od = __builtin_amdgcn_mfma_f32_32x32x16_bf16(pa2, PK(l2, h2), od, 0, 0, 0);
;     od = __builtin_amdgcn_mfma_f32_32x32x16_bf16(pa3, PK(l3, h3), od, 0, 0, 0);
;     ...
; }
; __device__ __forceinline__ void pv_d0(f32x16* o, int vb, bf16x8 pa0, bf16x8 pa1, bf16x8 pa2, bf16x8 pa3) {
;     pv_one<0>(o[0], vb, pa0, pa1, pa2, pa3); pv_one<1>(o[1], vb, pa0, pa1, pa2, pa3); pv_one<2>(o[2], vb, pa0, pa1, pa2, pa3); pv_one<3>(o[3], vb, pa0, pa1, pa2, pa3);
	s_nop 0
	v_mfma_f32_32x32x16_bf16 v[0:15], v[64:67], v[168:171], v[0:15]
	ds_read_b64_tr_b16 v[168:169], v172 offset:0x200
	ds_read_b64_tr_b16 v[170:171], v172 offset:0xa00
	v_mfma_f32_32x32x16_bf16 v[0:15], v[68:71], v[196:199], v[0:15]
	ds_read_b64_tr_b16 v[196:197], v172 offset:0x1200
	ds_read_b64_tr_b16 v[198:199], v172 offset:0x1a00
	v_mfma_f32_32x32x16_bf16 v[0:15], v[72:75], v[234:237], v[0:15]
	ds_read_b64_tr_b16 v[234:235], v172 offset:0x2200
	ds_read_b64_tr_b16 v[236:237], v172 offset:0x2a00
	v_mfma_f32_32x32x16_bf16 v[0:15], v[76:79], v[238:241], v[0:15]
	ds_read_b64_tr_b16 v[238:239], v172 offset:0x3200
	ds_read_b64_tr_b16 v[240:241], v172 offset:0x3a00
	s_waitcnt lgkmcnt(0)
	v_mfma_f32_32x32x16_bf16 v[48:63], v[64:67], v[168:171], v[48:63]
	ds_read_b64_tr_b16 v[168:169], v172 offset:0x400
	ds_read_b64_tr_b16 v[170:171], v172 offset:0xc00
	v_mfma_f32_32x32x16_bf16 v[48:63], v[68:71], v[196:199], v[48:63]
	ds_read_b64_tr_b16 v[196:197], v172 offset:0x1400
	ds_read_b64_tr_b16 v[198:199], v172 offset:0x1c00
	v_mfma_f32_32x32x16_bf16 v[48:63], v[72:75], v[234:237], v[48:63]
	ds_read_b64_tr_b16 v[234:235], v172 offset:0x2400
	ds_read_b64_tr_b16 v[236:237], v172 offset:0x2c00
	v_mfma_f32_32x32x16_bf16 v[48:63], v[76:79], v[238:241], v[48:63]
	ds_read_b64_tr_b16 v[238:239], v172 offset:0x3400
	ds_read_b64_tr_b16 v[240:241], v172 offset:0x3c00
	s_waitcnt lgkmcnt(0)
	v_mfma_f32_32x32x16_bf16 v[32:47], v[64:67], v[168:171], v[32:47]
	ds_read_b64_tr_b16 v[168:169], v172 offset:0x600
	ds_read_b64_tr_b16 v[170:171], v172 offset:0xe00
	v_mfma_f32_32x32x16_bf16 v[32:47], v[68:71], v[196:199], v[32:47]
	ds_read_b64_tr_b16 v[196:197], v172 offset:0x1600
	ds_read_b64_tr_b16 v[198:199], v172 offset:0x1e00
	v_mfma_f32_32x32x16_bf16 v[32:47], v[72:75], v[234:237], v[32:47]
	ds_read_b64_tr_b16 v[234:235], v172 offset:0x2600
	ds_read_b64_tr_b16 v[236:237], v172 offset:0x2e00
	v_mfma_f32_32x32x16_bf16 v[32:47], v[76:79], v[238:241], v[32:47]
	ds_read_b64_tr_b16 v[238:239], v172 offset:0x3600
	ds_read_b64_tr_b16 v[240:241], v172 offset:0x3e00
	s_waitcnt lgkmcnt(0)
	v_mfma_f32_32x32x16_bf16 v[16:31], v[64:67], v[168:171], v[16:31]
	v_max_f32_e32 v64, v97, v97
	v_max_f32_e32 v65, v96, v96
	v_max_f32_e32 v64, v65, v64
	v_max3_f32 v64, v64, v98, v99
	v_max3_f32 v64, v64, v100, v101
	v_max3_f32 v64, v64, v102, v103
	v_max3_f32 v64, v64, v104, v105
	v_mfma_f32_32x32x16_bf16 v[16:31], v[68:71], v[196:199], v[16:31]
	v_max3_f32 v64, v64, v106, v107
	v_max3_f32 v64, v64, v108, v109
	v_max3_f32 v64, v64, v110, v111
	v_max3_f32 v64, v64, v80, v81
	v_max3_f32 v64, v64, v82, v83
	v_max3_f32 v64, v64, v84, v85
	v_max3_f32 v64, v64, v86, v87
	v_mfma_f32_32x32x16_bf16 v[16:31], v[72:75], v[234:237], v[16:31]
	v_max3_f32 v64, v64, v88, v89
	v_max3_f32 v64, v64, v90, v91
	v_max3_f32 v64, v64, v92, v93
	v_max3_f32 v64, v64, v94, v95
	v_mov_b32_e32 v65, v64
	s_nop 1
	v_permlane32_swap_b32_e32 v64, v65
	v_max_f32_e32 v65, v65, v65
	v_max_f32_e32 v64, v64, v64
	v_mfma_f32_32x32x16_bf16 v[16:31], v[76:79], v[238:241], v[16:31]
	v_max_f32_e32 v64, v64, v65
	v_sub_f32_e32 v65, v64, v182
	s_mov_b32 s0, 0x41300000
	v_cmp_ge_f32_e32 vcc, s0, v65
	s_cmp_eq_u64 vcc, exec
	s_cbranch_scc0 .Latt_slow1
	v_mov_b32_e32 v184, v182
	v_mov_b32_e32 v233, 1.0
	v_cmp_eq_f32_e64 s[0:1], 0, v182
	s_cmp_eq_u64 s[0:1], exec
	s_cbranch_scc0 .LBB0_228
.LBB0_221:
	v_exp_f32_e32 v182, v98
	v_exp_f32_e32 v172, v96
	v_exp_f32_e32 v173, v97
	v_exp_f32_e32 v195, v99
	v_exp_f32_e32 v196, v100
	v_exp_f32_e32 v197, v101
	v_exp_f32_e32 v198, v102
	v_exp_f32_e32 v199, v103
	v_exp_f32_e32 v200, v104
	v_exp_f32_e32 v234, v105
	v_exp_f32_e32 v235, v106
	v_exp_f32_e32 v236, v107
	v_exp_f32_e32 v237, v108
	v_exp_f32_e32 v238, v109
	v_exp_f32_e32 v239, v110
	v_exp_f32_e32 v240, v111
	s_mul_i32 s0, s10, 0x6000
	s_add_i32 s16, s0, 0
	s_add_i32 s17, s16, s6
	s_add_i32 s18, s16, s8
	s_waitcnt vmcnt(0) lgkmcnt(0)
	s_barrier
	s_add_i32 s15, s7, s15
	s_setprio 1
	v_add_u32_e32 v68, s14, v207
	ds_read_b128 v[64:67], v68
	ds_read_b128 v[68:71], v68 offset:8192
	v_add_u32_e32 v186, s14, v210
	ds_read_b128 v[168:171], v186
	ds_read_b128 v[186:189], v186 offset:8192
	s_waitcnt lgkmcnt(0)
	v_mfma_f32_32x32x16_bf16 v[96:111], v[64:67], v[156:159], 0
	v_mfma_f32_32x32x16_bf16 v[64:79], v[68:71], v[156:159], 0
	v_mfma_f32_32x32x16_bf16 v[96:111], v[168:171], v[152:155], v[96:111]
	v_mfma_f32_32x32x16_bf16 v[64:79], v[186:189], v[152:155], v[64:79]
	v_add_u32_e32 v186, s14, v218
	ds_read_b128 v[168:171], v186
	ds_read_b128 v[186:189], v186 offset:8192
	s_mov_b32 m0, s17
	s_add_u32 s100, s72, 0x26580000
	s_addc_u32 s101, s73, 0
	global_load_lds_dwordx4 v178, s[100:101]
	s_waitcnt lgkmcnt(0)
	v_mfma_f32_32x32x16_bf16 v[96:111], v[168:171], v[148:151], v[96:111]
	v_mfma_f32_32x32x16_bf16 v[64:79], v[186:189], v[148:151], v[64:79]
	v_add_u32_e32 v186, s14, v221
	ds_read_b128 v[168:171], v186
	ds_read_b128 v[186:189], v186 offset:8192
	s_waitcnt lgkmcnt(0)
	v_mfma_f32_32x32x16_bf16 v[96:111], v[168:171], v[144:147], v[96:111]
	v_mfma_f32_32x32x16_bf16 v[64:79], v[186:189], v[144:147], v[64:79]
	v_add_u32_e32 v186, s14, v222
	ds_read_b128 v[168:171], v186
	ds_read_b128 v[186:189], v186 offset:8192
	s_add_i32 m0, s17, 0x400
	s_nop 0
	global_load_lds_dwordx4 v180, s[100:101]
	v_exp_f32_e32 v190, v88
	s_waitcnt lgkmcnt(0)
	v_mfma_f32_32x32x16_bf16 v[96:111], v[168:171], v[140:143], v[96:111]
	v_mfma_f32_32x32x16_bf16 v[64:79], v[186:189], v[140:143], v[64:79]
	v_add_u32_e32 v186, s14, v223
	ds_read_b128 v[168:171], v186
	ds_read_b128 v[186:189], v186 offset:8192
	v_exp_f32_e32 v191, v89
	s_waitcnt lgkmcnt(0)
; __device__ __forceinline__ void finishSM(f32x16& p0, f32x16& p1, float alpha, float& l_reg, bf16x8& pa0, bf16x8& pa1, bf16x8& pa2, bf16x8& pa3) {
; #pragma unroll
;     for (int r = 0; r < 16; ++r) p1[r] = __builtin_amdgcn_exp2f(p1[r]);
;     float ps = 0;
; #pragma unroll
;     for (int r = 0; r < 16; ++r) ps += p0[r];
; #pragma unroll
;     for (int r = 0; r < 16; ++r) ps += p1[r];
;     { auto rr = __builtin_amdgcn_permlane32_swap(__float_as_uint(ps), __float_as_uint(ps), false, false);
;       ps = __uint_as_float(rr[0]) + __uint_as_float(rr[1]); }
;     l_reg = l_reg * alpha + ps;
;     ...
;     PK4(p0, 0, pa0); PK4(p0, 8, pa1); PK4(p1, 0, pa2); PK4(p1, 8, pa3);
;     ...
; }
; __device__ __forceinline__ void qkt(f32x16& p0, f32x16& p1, const char* Kn, const bf16x8* qr, int r32, int hi) {
;     const char* Kr = Kn + KR_OFF;
;     p0 = f32x16{}; p1 = f32x16{};
;     __builtin_amdgcn_s_setprio(1);
; #pragma unroll
;     for (int d0 = 0; d0 < 8; ++d0) { const int cb = (d0 * 16 + hi * 8) * 2;
;         const bf16x8 b0 = *reinterpret_cast<const bf16x8*>(Kn + KNSWZ(r32, cb));
;         const bf16x8 b1 = *reinterpret_cast<const bf16x8*>(Kn + KNSWZ(32 + r32, cb));
;         p0 = __builtin_amdgcn_mfma_f32_32x32x16_bf16(b0, qr[d0], p0, 0, 0, 0);
;         p1 = __builtin_amdgcn_mfma_f32_32x32x16_bf16(b1, qr[d0], p1, 0, 0, 0); }
; #pragma unroll
;     for (int d0 = 0; d0 < 4; ++d0) { const int cb = (d0 * 16 + hi * 8) * 2;
;         const bf16x8 b0 = *reinterpret_cast<const bf16x8*>(Kr + KRSWZ(r32, cb));
;         const bf16x8 b1 = *reinterpret_cast<const bf16x8*>(Kr + KRSWZ(32 + r32, cb));
;         p0 = __builtin_amdgcn_mfma_f32_32x32x16_bf16(b0, qr[8 + d0], p0, 0, 0, 0);
;         p1 = __builtin_amdgcn_mfma_f32_32x32x16_bf16(b1, qr[8 + d0], p1, 0, 0, 0); }
; }
	v_mfma_f32_32x32x16_bf16 v[96:111], v[168:171], v[136:139], v[96:111]
	v_mfma_f32_32x32x16_bf16 v[64:79], v[186:189], v[136:139], v[64:79]
	v_add_u32_e32 v186, s14, v224
	ds_read_b128 v[168:171], v186
	ds_read_b128 v[186:189], v186 offset:8192
	s_mov_b32 m0, s15
	s_add_u32 s100, s72, 0x26580100
	s_addc_u32 s101, s73, 0
	global_load_lds_dwordx4 v176, s[100:101]
	v_exp_f32_e32 v192, v90
	s_waitcnt lgkmcnt(0)
	v_mfma_f32_32x32x16_bf16 v[96:111], v[168:171], v[132:135], v[96:111]
	v_mfma_f32_32x32x16_bf16 v[64:79], v[186:189], v[132:135], v[64:79]
	v_add_u32_e32 v186, s14, v225
	ds_read_b128 v[168:171], v186
	ds_read_b128 v[186:189], v186 offset:8192
	v_exp_f32_e32 v193, v91
	s_waitcnt lgkmcnt(0)
	v_mfma_f32_32x32x16_bf16 v[96:111], v[168:171], v[128:131], v[96:111]
	v_mfma_f32_32x32x16_bf16 v[64:79], v[186:189], v[128:131], v[64:79]
	v_add_u32_e32 v186, s14, v226
	ds_read_b128 v[168:171], v186 offset:16384
	ds_read_b128 v[186:189], v186 offset:20480
	s_add_i32 m0, s15, 0x400
	s_add_u32 s100, s72, 0x26580180
	s_addc_u32 s101, s73, 0
	global_load_lds_dwordx4 v176, s[100:101]
	v_exp_f32_e32 v241, v92
	s_waitcnt lgkmcnt(0)
	v_mfma_f32_32x32x16_bf16 v[96:111], v[168:171], v[124:127], v[96:111]
	v_mfma_f32_32x32x16_bf16 v[64:79], v[186:189], v[124:127], v[64:79]
	v_add_u32_e32 v186, s14, v227
	ds_read_b128 v[168:171], v186 offset:16384
	ds_read_b128 v[186:189], v186 offset:20480
	v_exp_f32_e32 v242, v93
	s_waitcnt lgkmcnt(0)
	v_mfma_f32_32x32x16_bf16 v[96:111], v[168:171], v[120:123], v[96:111]
	v_mfma_f32_32x32x16_bf16 v[64:79], v[186:189], v[120:123], v[64:79]
	v_add_u32_e32 v186, s14, v228
	ds_read_b128 v[168:171], v186 offset:16384
	ds_read_b128 v[186:189], v186 offset:20480
	s_add_i32 m0, s18, 0x4000
	s_add_u32 s100, s72, 0x21206000
	s_addc_u32 s101, s73, 0
	global_load_lds_dwordx4 v174, s[100:101]
	v_exp_f32_e32 v94, v94
	s_waitcnt lgkmcnt(0)
	v_mfma_f32_32x32x16_bf16 v[96:111], v[168:171], v[116:119], v[96:111]
	v_mfma_f32_32x32x16_bf16 v[64:79], v[186:189], v[116:119], v[64:79]
	v_add_u32_e32 v186, s14, v229
	ds_read_b128 v[168:171], v186 offset:16384
	ds_read_b128 v[186:189], v186 offset:20480
	v_exp_f32_e32 v95, v95
	s_waitcnt lgkmcnt(0)
	v_mfma_f32_32x32x16_bf16 v[96:111], v[168:171], v[112:115], v[96:111]
	v_exp_f32_e32 v168, v80
	v_add_f32_e32 v80, 0, v172
	v_add_f32_e32 v80, v173, v80
	v_add_f32_e32 v80, v182, v80
	v_add_f32_e32 v80, v195, v80
	v_add_f32_e32 v80, v196, v80
	v_add_f32_e32 v80, v197, v80
	v_add_f32_e32 v80, v198, v80
	v_add_f32_e32 v80, v199, v80
	v_add_f32_e32 v80, v200, v80
	v_add_f32_e32 v80, v234, v80
	v_add_f32_e32 v80, v235, v80
	v_add_f32_e32 v80, v236, v80
	v_add_f32_e32 v80, v237, v80
	v_exp_f32_e32 v169, v81
	v_add_f32_e32 v80, v238, v80
	v_exp_f32_e32 v170, v82
	v_add_f32_e32 v80, v239, v80
	v_exp_f32_e32 v171, v83
	v_add_f32_e32 v80, v240, v80
	v_mfma_f32_32x32x16_bf16 v[64:79], v[186:189], v[112:115], v[64:79]
	v_exp_f32_e32 v186, v84
	v_add_f32_e32 v80, v168, v80
	v_exp_f32_e32 v187, v85
	v_add_f32_e32 v80, v169, v80
	v_exp_f32_e32 v188, v86
	v_add_f32_e32 v80, v170, v80
	v_exp_f32_e32 v189, v87
	v_add_f32_e32 v80, v171, v80
	v_add_f32_e32 v80, v186, v80
	v_add_f32_e32 v80, v187, v80
	v_add_f32_e32 v80, v188, v80
	v_add_f32_e32 v80, v189, v80
	v_add_f32_e32 v80, v190, v80
	v_add_f32_e32 v80, v191, v80
	v_add_f32_e32 v80, v192, v80
	v_add_f32_e32 v80, v193, v80
	v_add_f32_e32 v80, v241, v80
	v_add_f32_e32 v80, v242, v80
	v_add_f32_e32 v80, v94, v80
	v_add_f32_e32 v80, v95, v80
	v_mov_b32_e32 v81, v80
	v_cvt_pk_bf16_f32 v82, v172, v173
	v_cvt_pk_bf16_f32 v83, v182, v195
	v_cvt_pk_bf16_f32 v84, v196, v197
	s_nop 1
	v_permlane32_swap_b32_e32 v80, v81
	v_cvt_pk_bf16_f32 v85, v198, v199
	v_permlane32_swap_b32_e32 v82, v84
	v_cvt_pk_bf16_f32 v86, v200, v234
	v_cvt_pk_bf16_f32 v87, v235, v236
	v_cvt_pk_bf16_f32 v88, v237, v238
	v_cvt_pk_bf16_f32 v89, v239, v240
	v_cvt_pk_bf16_f32 v90, v168, v169
	v_cvt_pk_bf16_f32 v91, v170, v171
	v_cvt_pk_bf16_f32 v92, v186, v187
	v_cvt_pk_bf16_f32 v93, v188, v189
	v_cvt_pk_bf16_f32 v168, v190, v191
	v_cvt_pk_bf16_f32 v169, v192, v193
	v_cvt_pk_bf16_f32 v170, v241, v242
	v_cvt_pk_bf16_f32 v171, v94, v95
	v_permlane32_swap_b32_e32 v83, v85
	v_permlane32_swap_b32_e32 v86, v88
	v_permlane32_swap_b32_e32 v87, v89
	v_permlane32_swap_b32_e32 v90, v92
	v_permlane32_swap_b32_e32 v91, v93
	v_permlane32_swap_b32_e32 v168, v170
	v_permlane32_swap_b32_e32 v169, v171
	s_setprio 0
	v_lshl_add_u32 v94, s13, 14, v205
	ds_read_b64_tr_b16 v[186:187], v94 offset:0
	ds_read_b64_tr_b16 v[188:189], v94 offset:0x800
	ds_read_b64_tr_b16 v[190:191], v94 offset:0x1000
	ds_read_b64_tr_b16 v[192:193], v94 offset:0x1800
	ds_read_b64_tr_b16 v[196:197], v94 offset:0x2000
	ds_read_b64_tr_b16 v[198:199], v94 offset:0x2800
	ds_read_b64_tr_b16 v[234:235], v94 offset:0x3000
	ds_read_b64_tr_b16 v[236:237], v94 offset:0x3800
	s_waitcnt lgkmcnt(0)
; #define SBAR() __builtin_amdgcn_sched_barrier(0)
; template <bool FIRST>
; __device__ __forceinline__ void partialSM(f32x16& p0, f32x16& p1, float& m_reg, float& mn, float& alpha) {
;     float pmax = p0[0];
; #pragma unroll
;     for (int r = 1; r < 16; ++r) pmax = fmaxf(pmax, p0[r]);
; #pragma unroll
;     for (int r = 0; r < 16; ++r) pmax = fmaxf(pmax, p1[r]);
;     { auto rr = __builtin_amdgcn_permlane32_swap(__float_as_uint(pmax), __float_as_uint(pmax), false, false);
;       pmax = fmaxf(__uint_as_float(rr[0]), __uint_as_float(rr[1])); }
;     if (FIRST) { mn = (fabsf(pmax) <= THRL) ? 0.f : pmax; m_reg = mn; alpha = 1.f; }
;     else if (__builtin_expect(__all(pmax - m_reg <= THRL), 1)) { mn = m_reg; alpha = 1.f; }
;     else { mn = fmaxf(m_reg, pmax); alpha = __builtin_amdgcn_exp2f(m_reg - mn); m_reg = mn; }
;     if (!__builtin_expect(__all(mn == 0.f), 1)) {
; #pragma unroll
;         for (int r = 0; r < 16; ++r) p0[r] = p0[r] - mn;
; #pragma unroll
;         for (int r = 0; r < 16; ++r) p1[r] = p1[r] - mn; }
; #pragma unroll
;     for (int r = 0; r < 16; ++r) p0[r] = __builtin_amdgcn_exp2f(p0[r]);
; }
; template <int D0> __device__ __forceinline__ void pv_one(f32x16& od, int vb, bf16x8 pa0, bf16x8 pa1, bf16x8 pa2, bf16x8 pa3) {
;     const s16x4 l0 = tr_read<v_rd_off(D0, 0, 0)>(vb), h0 = tr_read<v_rd_off(D0, 0, 1)>(vb), l1 = tr_read<v_rd_off(D0, 1, 0)>(vb), h1 = tr_read<v_rd_off(D0, 1, 1)>(vb);
;     const s16x4 l2 = tr_read<v_rd_off(D0, 2, 0)>(vb), h2 = tr_read<v_rd_off(D0, 2, 1)>(vb), l3 = tr_read<v_rd_off(D0, 3, 0)>(vb), h3 = tr_read<v_rd_off(D0, 3, 1)>(vb);
;     asm volatile("s_waitcnt lgkmcnt(0)" ::: "memory"); SBAR();
;     ...
;     od = __builtin_amdgcn_mfma_f32_32x32x16_bf16(pa0, PK(l0, h0), od, 0, 0, 0);
;     od = __builtin_amdgcn_mfma_f32_32x32x16_bf16(pa1, PK(l1, h1), od, 0, 0, 0);
;     od = __builtin_amdgcn_mfma_f32_32x32x16_bf16(pa2, PK(l2, h2), od, 0, 0, 0);
;     od = __builtin_amdgcn_mfma_f32_32x32x16_bf16(pa3, PK(l3, h3), od, 0, 0, 0);
;     ...
; }
; __device__ __forceinline__ void pv_d0(f32x16* o, int vb, bf16x8 pa0, bf16x8 pa1, bf16x8 pa2, bf16x8 pa3) {
;     pv_one<0>(o[0], vb, pa0, pa1, pa2, pa3); pv_one<1>(o[1], vb, pa0, pa1, pa2, pa3); pv_one<2>(o[2], vb, pa0, pa1, pa2, pa3); pv_one<3>(o[3], vb, pa0, pa1, pa2, pa3);
	s_nop 0
	v_mfma_f32_32x32x16_bf16 v[0:15], v[82:85], v[186:189], v[0:15]
	ds_read_b64_tr_b16 v[186:187], v94 offset:0x200
	ds_read_b64_tr_b16 v[188:189], v94 offset:0xa00
	v_mfma_f32_32x32x16_bf16 v[0:15], v[86:89], v[190:193], v[0:15]
	ds_read_b64_tr_b16 v[190:191], v94 offset:0x1200
	ds_read_b64_tr_b16 v[192:193], v94 offset:0x1a00
	v_mfma_f32_32x32x16_bf16 v[0:15], v[90:93], v[196:199], v[0:15]
	ds_read_b64_tr_b16 v[196:197], v94 offset:0x2200
	ds_read_b64_tr_b16 v[198:199], v94 offset:0x2a00
	v_mfma_f32_32x32x16_bf16 v[0:15], v[168:171], v[234:237], v[0:15]
	ds_read_b64_tr_b16 v[234:235], v94 offset:0x3200
	ds_read_b64_tr_b16 v[236:237], v94 offset:0x3a00
	s_waitcnt lgkmcnt(0)
	v_mfma_f32_32x32x16_bf16 v[48:63], v[82:85], v[186:189], v[48:63]
	ds_read_b64_tr_b16 v[186:187], v94 offset:0x400
	ds_read_b64_tr_b16 v[188:189], v94 offset:0xc00
	v_mfma_f32_32x32x16_bf16 v[48:63], v[86:89], v[190:193], v[48:63]
	ds_read_b64_tr_b16 v[190:191], v94 offset:0x1400
	ds_read_b64_tr_b16 v[192:193], v94 offset:0x1c00
	v_mfma_f32_32x32x16_bf16 v[48:63], v[90:93], v[196:199], v[48:63]
	ds_read_b64_tr_b16 v[196:197], v94 offset:0x2400
	ds_read_b64_tr_b16 v[198:199], v94 offset:0x2c00
	v_mfma_f32_32x32x16_bf16 v[48:63], v[168:171], v[234:237], v[48:63]
	ds_read_b64_tr_b16 v[234:235], v94 offset:0x3400
	ds_read_b64_tr_b16 v[236:237], v94 offset:0x3c00
	s_waitcnt lgkmcnt(0)
	v_mfma_f32_32x32x16_bf16 v[32:47], v[82:85], v[186:189], v[32:47]
	ds_read_b64_tr_b16 v[186:187], v94 offset:0x600
	ds_read_b64_tr_b16 v[188:189], v94 offset:0xe00
	v_mfma_f32_32x32x16_bf16 v[32:47], v[86:89], v[190:193], v[32:47]
	ds_read_b64_tr_b16 v[190:191], v94 offset:0x1600
	ds_read_b64_tr_b16 v[192:193], v94 offset:0x1e00
	v_mfma_f32_32x32x16_bf16 v[32:47], v[90:93], v[196:199], v[32:47]
	ds_read_b64_tr_b16 v[196:197], v94 offset:0x2600
	ds_read_b64_tr_b16 v[198:199], v94 offset:0x2e00
	v_mfma_f32_32x32x16_bf16 v[32:47], v[168:171], v[234:237], v[32:47]
	ds_read_b64_tr_b16 v[234:235], v94 offset:0x3600
	ds_read_b64_tr_b16 v[236:237], v94 offset:0x3e00
	s_waitcnt lgkmcnt(0)
	v_mfma_f32_32x32x16_bf16 v[16:31], v[82:85], v[186:189], v[16:31]
	v_max_f32_e32 v82, v97, v97
	v_max_f32_e32 v83, v96, v96
	v_max_f32_e32 v82, v83, v82
	v_max3_f32 v82, v82, v98, v99
	v_max3_f32 v82, v82, v100, v101
	v_max3_f32 v82, v82, v102, v103
	v_max3_f32 v82, v82, v104, v105
	v_mfma_f32_32x32x16_bf16 v[16:31], v[86:89], v[190:193], v[16:31]
	v_max3_f32 v82, v82, v106, v107
	v_max3_f32 v82, v82, v108, v109
	v_max3_f32 v82, v82, v110, v111
	v_max3_f32 v82, v82, v64, v65
	v_max3_f32 v82, v82, v66, v67
	v_max3_f32 v82, v82, v68, v69
	v_max3_f32 v82, v82, v70, v71
	v_mfma_f32_32x32x16_bf16 v[16:31], v[90:93], v[196:199], v[16:31]
	v_max3_f32 v82, v82, v72, v73
	v_max3_f32 v82, v82, v74, v75
	v_max3_f32 v82, v82, v76, v77
	v_max3_f32 v82, v82, v78, v79
	v_mov_b32_e32 v83, v82
	s_nop 1
	v_permlane32_swap_b32_e32 v82, v83
	v_max_f32_e32 v83, v83, v83
	v_max_f32_e32 v82, v82, v82
	v_mfma_f32_32x32x16_bf16 v[16:31], v[168:171], v[234:237], v[16:31]
	v_max_f32_e32 v82, v82, v83
	v_sub_f32_e32 v83, v82, v184
	s_mov_b32 s0, 0x41300000
	v_cmp_ge_f32_e32 vcc, s0, v83
	s_cmp_eq_u64 vcc, exec
	s_cbranch_scc0 .Latt_slow2
	v_mov_b32_e32 v182, v184
	v_cmp_eq_f32_e64 s[0:1], 0, v182
	s_cmp_eq_u64 s[0:1], exec
	s_cbranch_scc0 .LBB0_229
	v_mov_b32_e32 v184, 1.0

; template <bool FIRST>
; __device__ __forceinline__ void partialSM(f32x16& p0, f32x16& p1, float& m_reg, float& mn, float& alpha) {
;     ...
;     if (FIRST) { mn = (fabsf(pmax) <= THRL) ? 0.f : pmax; m_reg = mn; alpha = 1.f; }
;     else if (__builtin_expect(__all(pmax - m_reg <= THRL), 1)) { mn = m_reg; alpha = 1.f; }
;     else { mn = fmaxf(m_reg, pmax); alpha = __builtin_amdgcn_exp2f(m_reg - mn); m_reg = mn; }
;     if (!__builtin_expect(__all(mn == 0.f), 1)) {
; #pragma unroll
;         for (int r = 0; r < 16; ++r) p0[r] = p0[r] - mn;
; #pragma unroll
;         for (int r = 0; r < 16; ++r) p1[r] = p1[r] - mn; }
.Latt_slow1:
	v_max_f32_e32 v65, v182, v182
	s_cselect_b64 vcc, -1, 0
	v_max_f32_e32 v64, v65, v64
	v_cndmask_b32_e32 v184, v64, v182, vcc
	v_cmp_eq_f32_e64 s[0:1], 0, v184
	s_cmp_eq_u64 s[0:1], exec
	s_cbranch_scc0 .LBB0_228
.LBB0_217:
	v_sub_f32_e32 v64, v182, v64
	v_exp_f32_e32 v64, v64
	s_nop 0
	v_cndmask_b32_e64 v233, v64, 1.0, vcc
	v_cmp_gt_f32_e32 vcc, 1.0, v233
	s_cbranch_vccz .LBB0_221
	s_and_saveexec_b64 s[0:1], s[38:39]
	ds_write_b32 v202, v233 offset:128
	s_or_b64 exec, exec, s[0:1]
	s_waitcnt lgkmcnt(0)
	v_add_u32_e32 v76, s5, v160
	ds_read_b128 v[64:67], v76 offset:224
	ds_read_b128 v[68:71], v76 offset:192
	ds_read_b128 v[72:75], v76 offset:160
	ds_read_b128 v[76:79], v76 offset:128
	s_waitcnt lgkmcnt(0)
	v_pk_mul_f32 v[12:13], v[12:13], v[64:65]
	v_pk_mul_f32 v[8:9], v[8:9], v[68:69]
	v_pk_mul_f32 v[4:5], v[4:5], v[72:73]
	v_pk_mul_f32 v[14:15], v[14:15], v[66:67]
	v_pk_mul_f32 v[10:11], v[10:11], v[70:71]
	v_pk_mul_f32 v[6:7], v[6:7], v[74:75]
	v_pk_mul_f32 v[2:3], v[2:3], v[78:79]
	v_pk_mul_f32 v[0:1], v[0:1], v[76:77]
	v_pk_mul_f32 v[60:61], v[60:61], v[64:65]
	v_pk_mul_f32 v[56:57], v[56:57], v[68:69]
	v_pk_mul_f32 v[52:53], v[52:53], v[72:73]
	v_pk_mul_f32 v[62:63], v[62:63], v[66:67]
	v_pk_mul_f32 v[58:59], v[58:59], v[70:71]
	v_pk_mul_f32 v[54:55], v[54:55], v[74:75]
	v_pk_mul_f32 v[50:51], v[50:51], v[78:79]
	v_pk_mul_f32 v[48:49], v[48:49], v[76:77]
	v_pk_mul_f32 v[44:45], v[44:45], v[64:65]
	v_pk_mul_f32 v[40:41], v[40:41], v[68:69]
	v_pk_mul_f32 v[36:37], v[36:37], v[72:73]
	v_pk_mul_f32 v[46:47], v[46:47], v[66:67]
	v_pk_mul_f32 v[42:43], v[42:43], v[70:71]
	v_pk_mul_f32 v[38:39], v[38:39], v[74:75]
	v_pk_mul_f32 v[34:35], v[34:35], v[78:79]
	v_pk_mul_f32 v[32:33], v[32:33], v[76:77]
	v_pk_mul_f32 v[28:29], v[28:29], v[64:65]
	v_pk_mul_f32 v[24:25], v[24:25], v[68:69]
	v_pk_mul_f32 v[20:21], v[20:21], v[72:73]
	v_pk_mul_f32 v[30:31], v[30:31], v[66:67]
	v_pk_mul_f32 v[26:27], v[26:27], v[70:71]
	v_pk_mul_f32 v[22:23], v[22:23], v[74:75]
	v_pk_mul_f32 v[18:19], v[18:19], v[78:79]
	v_pk_mul_f32 v[16:17], v[16:17], v[76:77]
	s_branch .LBB0_221
.Latt_slow2:
	v_max_f32_e32 v83, v184, v184
	s_cselect_b64 vcc, -1, 0
	v_max_f32_e32 v82, v83, v82
	v_cndmask_b32_e32 v182, v82, v184, vcc
	v_cmp_eq_f32_e64 s[0:1], 0, v182
	s_cmp_eq_u64 s[0:1], exec
	s_cbranch_scc0 .LBB0_229
.LBB0_222:
	v_sub_f32_e32 v82, v184, v82
	v_exp_f32_e32 v82, v82
	s_nop 0
	v_cndmask_b32_e64 v184, v82, 1.0, vcc
	v_cmp_gt_f32_e32 vcc, 1.0, v184
	s_cbranch_vccz .LBB0_226
	s_and_saveexec_b64 s[0:1], s[38:39]
	ds_write_b32 v202, v184 offset:128
	s_or_b64 exec, exec, s[0:1]
	s_waitcnt lgkmcnt(0)
	v_add_u32_e32 v94, s5, v160
	ds_read_b128 v[82:85], v94 offset:224
	ds_read_b128 v[86:89], v94 offset:192
	ds_read_b128 v[90:93], v94 offset:160
	ds_read_b128 v[168:171], v94 offset:128
	s_waitcnt lgkmcnt(0)
	v_pk_mul_f32 v[12:13], v[12:13], v[82:83]
	v_pk_mul_f32 v[8:9], v[8:9], v[86:87]
	v_pk_mul_f32 v[4:5], v[4:5], v[90:91]
	v_pk_mul_f32 v[14:15], v[14:15], v[84:85]
	v_pk_mul_f32 v[10:11], v[10:11], v[88:89]
	v_pk_mul_f32 v[6:7], v[6:7], v[92:93]
	v_pk_mul_f32 v[2:3], v[2:3], v[170:171]
	v_pk_mul_f32 v[0:1], v[0:1], v[168:169]
	v_pk_mul_f32 v[60:61], v[60:61], v[82:83]
	v_pk_mul_f32 v[56:57], v[56:57], v[86:87]
	v_pk_mul_f32 v[52:53], v[52:53], v[90:91]
	v_pk_mul_f32 v[62:63], v[62:63], v[84:85]
	v_pk_mul_f32 v[58:59], v[58:59], v[88:89]
	v_pk_mul_f32 v[54:55], v[54:55], v[92:93]
	v_pk_mul_f32 v[50:51], v[50:51], v[170:171]
	v_pk_mul_f32 v[48:49], v[48:49], v[168:169]
	v_pk_mul_f32 v[44:45], v[44:45], v[82:83]
	v_pk_mul_f32 v[40:41], v[40:41], v[86:87]
	v_pk_mul_f32 v[36:37], v[36:37], v[90:91]
	v_pk_mul_f32 v[46:47], v[46:47], v[84:85]
	v_pk_mul_f32 v[42:43], v[42:43], v[88:89]
	v_pk_mul_f32 v[38:39], v[38:39], v[92:93]
	v_pk_mul_f32 v[34:35], v[34:35], v[170:171]
	v_pk_mul_f32 v[32:33], v[32:33], v[168:169]
	v_pk_mul_f32 v[28:29], v[28:29], v[82:83]
	v_pk_mul_f32 v[24:25], v[24:25], v[86:87]
	v_pk_mul_f32 v[20:21], v[20:21], v[90:91]
	v_pk_mul_f32 v[30:31], v[30:31], v[84:85]
	v_pk_mul_f32 v[26:27], v[26:27], v[88:89]
	v_pk_mul_f32 v[22:23], v[22:23], v[92:93]
	v_pk_mul_f32 v[18:19], v[18:19], v[170:171]
	v_pk_mul_f32 v[16:17], v[16:17], v[168:169]
	s_branch .LBB0_226
